# attention phase-3 loop: K/V frags prefetched, no canonicalize max, bfe/and mask, PV MFMAs interleaved with exp
# speedup vs baseline: 1.0117x; 1.0117x over previous
.LBB0_801:
	s_or_b64 exec, exec, s[16:17]
	s_waitcnt vmcnt(1)
	v_and_b32_e32 v10, 0xffffffc0, v2
	v_and_b32_e32 v16, 31, v2
	v_bfe_u32 v17, v2, 5, 1
	v_add_u32_e32 v2, 1, v18
	v_cndmask_b32_e64 v111, v2, 33, s[14:15]
	v_or_b32_e32 v2, v19, v16
	v_ashrrev_i32_e32 v3, 31, v2
	v_lshl_add_u32 v126, v0, 8, v10
	s_waitcnt vmcnt(0)
	v_lshlrev_b64 v[8:9], 10, v[2:3]
	v_ashrrev_i32_e32 v127, 31, v126
	v_lshlrev_b64 v[2:3], 11, v[2:3]
	v_lshl_add_u64 v[8:9], s[8:9], 0, v[8:9]
	v_lshlrev_b64 v[10:11], 1, v[126:127]
	v_lshl_add_u64 v[130:131], s[88:89], 0, v[2:3]
	v_lshl_add_u64 v[8:9], v[8:9], 0, v[10:11]
	v_lshlrev_b32_e32 v0, 3, v17
	v_lshlrev_b32_e32 v132, 4, v17
	v_mov_b32_e32 v133, v1
	v_lshl_add_u64 v[2:3], v[130:131], 0, v[10:11]
	v_lshl_add_u64 v[8:9], v[8:9], 0, v[132:133]
	v_lshl_add_u64 v[2:3], v[2:3], 0, v[0:1]
	s_mov_b64 s[16:17], 0x12e80400
	global_load_dwordx4 v[80:83], v[8:9], off
	global_load_dwordx4 v[84:87], v[8:9], off offset:32
	global_load_dwordx4 v[88:91], v[8:9], off offset:64
	global_load_dwordx4 v[92:95], v[8:9], off offset:96
	v_lshl_add_u64 v[8:9], v[2:3], 0, s[16:17]
	s_mov_b32 s16, 0x12e80000
	v_add_co_u32_e32 v2, vcc, s16, v2
	v_mov_b32_e32 v109, v1
	s_nop 0
	v_addc_co_u32_e32 v3, vcc, 0, v3, vcc
	global_load_dwordx2 v[124:125], v[8:9], off offset:16
	global_load_dwordx2 v[122:123], v[8:9], off offset:32
	global_load_dwordx2 v[120:121], v[8:9], off offset:48
	global_load_dwordx2 v[118:119], v[8:9], off offset:64
	global_load_dwordx2 v[128:129], v[2:3], off offset:1024
	global_load_dwordx2 v[116:117], v[8:9], off offset:80
	global_load_dwordx2 v[114:115], v[8:9], off offset:96
	global_load_dwordx2 v[112:113], v[8:9], off offset:112
	v_lshl_add_u64 v[2:3], v[4:5], 0, v[106:107]
	v_lshl_add_u64 v[2:3], v[2:3], 0, v[108:109]
	v_cndmask_b32_e64 v0, v145, v151, s[14:15]
	v_cmp_lt_u32_e32 vcc, 1, v111
	global_load_dwordx4 v[8:11], v[2:3], off
	v_mad_i64_i32 v[2:3], s[14:15], v0, v104, 0
	v_cndmask_b32_e64 v0, 0, 64, vcc
	v_lshl_add_u64 v[2:3], v[2:3], 1, v[6:7]
	v_add_u32_e32 v6, v0, v104
	v_ashrrev_i32_e32 v7, 31, v6
	v_lshlrev_b64 v[6:7], 7, v[6:7]
	v_add_u32_e32 v133, -1, v111
	v_lshl_add_u64 v[6:7], v[4:5], 0, v[6:7]
	v_min_u32_e32 v18, 2, v133
	v_lshl_add_u64 v[6:7], v[6:7], 0, v[108:109]
	v_lshlrev_b32_e32 v0, 1, v0
	global_load_dwordx4 v[48:51], v[6:7], off
	v_lshl_add_u64 v[6:7], v[2:3], 0, v[0:1]
	v_lshlrev_b32_e32 v0, 7, v18
	v_lshl_add_u64 v[134:135], v[2:3], 0, v[108:109]
	v_lshl_add_u64 v[2:3], v[2:3], 0, v[0:1]
	v_lshl_add_u64 v[6:7], v[6:7], 0, v[108:109]
	v_lshl_add_u64 v[2:3], v[2:3], 0, v[108:109]
	global_load_dwordx4 v[52:55], v[6:7], off
	global_load_dwordx4 v[100:103], v[2:3], off
	v_lshl_add_u32 v6, v18, 6, v104
	v_ashrrev_i32_e32 v7, 31, v6
	v_lshlrev_b64 v[6:7], 7, v[6:7]
	global_load_dwordx4 v[12:15], v[134:135], off
	v_lshl_add_u64 v[6:7], v[4:5], 0, v[6:7]
	v_lshl_add_u64 v[6:7], v[6:7], 0, v[108:109]
	global_load_dwordx4 v[96:99], v[6:7], off
	v_mov_b32_e32 v2, v1
	v_mov_b32_e32 v3, v1
	v_lshlrev_b32_e32 v136, 2, v17
	v_lshl_add_u64 v[138:139], v[4:5], 0, v[108:109]
	v_mul_u32_u24_e32 v109, 0x90, v16
	v_mad_u32_u24 v152, v16, s43, v141
	v_mov_b32_e32 v0, v1
	v_mov_b32_e32 v4, v1
	v_mov_b32_e32 v5, v1
	v_mov_b32_e32 v6, v1
	v_mov_b32_e32 v7, v1
	s_mov_b32 s19, 0
	v_mov_b32_e32 v154, 0xf149f2ca
	v_mov_b32_e32 v153, 0
	s_mov_b64 s[14:15], 0
	s_waitcnt vmcnt(5)
	ds_write_b128 v105, v[8:11]
	s_waitcnt vmcnt(1)
	ds_write_b128 v143, v[12:15]
	v_mov_b32_e32 v14, v1
	v_mov_b32_e32 v15, v1
	v_mov_b32_e32 v8, v1
	v_mov_b32_e32 v9, v1
	v_mov_b32_e32 v10, v1
	v_mov_b32_e32 v11, v1
	v_mov_b32_e32 v12, v1
	v_mov_b32_e32 v13, v1
	v_mov_b64_e32 v[30:31], v[14:15]
	v_mov_b64_e32 v[46:47], v[14:15]
	v_mov_b64_e32 v[28:29], v[12:13]
	v_mov_b64_e32 v[26:27], v[10:11]
	v_mov_b64_e32 v[24:25], v[8:9]
	v_mov_b64_e32 v[22:23], v[6:7]
	v_mov_b64_e32 v[20:21], v[4:5]
	v_mov_b64_e32 v[18:19], v[2:3]
	v_mov_b64_e32 v[16:17], v[0:1]
	v_mov_b64_e32 v[44:45], v[12:13]
	v_mov_b64_e32 v[42:43], v[10:11]
	v_mov_b64_e32 v[40:41], v[8:9]
	v_mov_b64_e32 v[38:39], v[6:7]
	v_mov_b64_e32 v[36:37], v[4:5]
	v_mov_b64_e32 v[34:35], v[2:3]
	v_mov_b64_e32 v[32:33], v[0:1]
	s_waitcnt lgkmcnt(0)
	s_barrier
	s_branch .LBB0_803
.LBB0_803:
	s_add_i32 s18, s19, 1
	v_cmp_lt_i32_e32 vcc, s18, v111
	s_and_saveexec_b64 s[16:17], vcc
	s_cbranch_execz .LBB0_805
	s_bitcmp1_b32 s18, 0
	s_cselect_b32 s20, 0x4800, 0
	v_add_u32_e32 v0, s20, v105
	ds_write_b128 v0, v[48:51]
	ds_write_b128 v0, v[52:55] offset:9216
.LBB0_805:
	s_or_b64 exec, exec, s[16:17]
	s_add_i32 s16, s19, 3
	v_min_i32_e32 v0, s16, v133
	v_lshlrev_b32_e32 v6, 6, v0
	v_add_u32_e32 v2, v6, v104
	s_bitcmp1_b32 s19, 0
	s_mov_b32 s16, 0x23800
	v_ashrrev_i32_e32 v3, 31, v2
	s_cselect_b32 s16, s16, 0x1f000
	v_lshlrev_b64 v[2:3], 7, v[2:3]
	v_ashrrev_i32_e32 v7, 31, v6
	v_or_b32_e32 v0, s16, v132
	v_lshl_add_u64 v[2:3], v[138:139], 0, v[2:3]
	v_lshl_add_u64 v[6:7], v[6:7], 1, v[134:135]
	v_add_u32_e32 v0, v0, v109
	global_load_dwordx4 v[2:5], v[2:3], off
	s_nop 0
	global_load_dwordx4 v[6:9], v[6:7], off
	ds_read_b128 v[166:169], v0
	ds_read_b128 v[170:173], v0 offset:32
	ds_read_b128 v[174:177], v0 offset:64
	ds_read_b128 v[178:181], v0 offset:96
	ds_read_b128 v[182:185], v0 offset:4608
	ds_read_b128 v[186:189], v0 offset:4640
	ds_read_b128 v[190:193], v0 offset:4672
	ds_read_b128 v[194:197], v0 offset:4704
	ds_read_b64 v[158:159], v152
	v_lshlrev_b32_e32 v0, 1, v136
	v_add3_u32 v13, s16, v109, v0
	v_add_u32_e32 v15, 0x2000, v13
	v_add_u32_e32 v13, 0x3000, v13
	s_waitcnt lgkmcnt(8)
	v_mfma_f32_32x32x16_bf16 v[64:79], v[166:169], v[80:83], 0
	s_waitcnt lgkmcnt(7)
	v_mfma_f32_32x32x16_bf16 v[64:79], v[170:173], v[84:87], v[64:79]
	s_waitcnt lgkmcnt(6)
	v_mfma_f32_32x32x16_bf16 v[64:79], v[174:177], v[88:91], v[64:79]
	s_waitcnt lgkmcnt(5)
	v_mfma_f32_32x32x16_bf16 v[64:79], v[178:181], v[92:95], v[64:79]
	s_waitcnt lgkmcnt(4)
	v_mfma_f32_32x32x16_bf16 v[48:63], v[182:185], v[80:83], 0
	s_waitcnt lgkmcnt(3)
	v_mfma_f32_32x32x16_bf16 v[48:63], v[186:189], v[84:87], v[48:63]
	s_waitcnt lgkmcnt(2)
	v_mfma_f32_32x32x16_bf16 v[48:63], v[190:193], v[88:91], v[48:63]
	s_waitcnt lgkmcnt(1)
	v_mfma_f32_32x32x16_bf16 v[48:63], v[194:197], v[92:95], v[48:63]
	ds_read2_b64 v[166:169], v15 offset0:128 offset1:130
	ds_read2_b64 v[182:185], v13 offset0:192 offset1:194
	ds_read2_b64 v[170:173], v15 offset0:132 offset1:134
	ds_read2_b64 v[186:189], v13 offset0:196 offset1:198
	ds_read2_b64 v[174:177], v15 offset0:136 offset1:138
	ds_read2_b64 v[190:193], v13 offset0:200 offset1:202
	ds_read2_b64 v[178:181], v15 offset0:140 offset1:142
	ds_read2_b64 v[194:197], v13 offset0:204 offset1:206
	v_max3_f32 v244, v64, v65, v66
	v_max3_f32 v244, v244, v67, v68
	v_max3_f32 v244, v244, v69, v70
	v_max3_f32 v244, v244, v71, v72
	v_max3_f32 v244, v244, v73, v74
	v_max3_f32 v244, v244, v75, v76
	v_max3_f32 v244, v244, v77, v78
	v_max_f32_e32 v244, v244, v79
	v_max3_f32 v245, v48, v49, v50
	v_max3_f32 v245, v245, v51, v52
	v_max3_f32 v245, v245, v53, v54
	v_max3_f32 v245, v245, v55, v56
	v_max3_f32 v245, v245, v57, v58
	v_max3_f32 v245, v245, v59, v60
	v_max3_f32 v245, v245, v61, v62
	v_max_f32_e32 v245, v245, v63
	v_max_f32_e32 v244, v244, v245
	ds_bpermute_b32 v12, v234, v244
	v_mov_b32_e32 v10, 0
	s_waitcnt lgkmcnt(0)
	v_max3_f32 v12, v154, v244, v12
	v_sub_f32_e32 v242, v154, v12
	v_exp_f32_e32 v242, v242
	v_cmp_neq_f32_e32 vcc, v12, v154
	v_lshrrev_b32_e32 v158, v136, v158
	v_lshrrev_b32_e32 v159, v136, v159
	s_cbranch_vccz .Lattn3_nors
	v_pk_mul_f32 v[46:47], v[46:47], v[242:243] op_sel_hi:[1,0]
	v_pk_mul_f32 v[44:45], v[44:45], v[242:243] op_sel_hi:[1,0]
	v_pk_mul_f32 v[42:43], v[42:43], v[242:243] op_sel_hi:[1,0]
	v_pk_mul_f32 v[40:41], v[40:41], v[242:243] op_sel_hi:[1,0]
	v_pk_mul_f32 v[38:39], v[38:39], v[242:243] op_sel_hi:[1,0]
	v_pk_mul_f32 v[36:37], v[36:37], v[242:243] op_sel_hi:[1,0]
	v_pk_mul_f32 v[34:35], v[34:35], v[242:243] op_sel_hi:[1,0]
	v_pk_mul_f32 v[32:33], v[32:33], v[242:243] op_sel_hi:[1,0]
	v_pk_mul_f32 v[30:31], v[30:31], v[242:243] op_sel_hi:[1,0]
	v_pk_mul_f32 v[28:29], v[28:29], v[242:243] op_sel_hi:[1,0]
	v_pk_mul_f32 v[26:27], v[26:27], v[242:243] op_sel_hi:[1,0]
	v_pk_mul_f32 v[24:25], v[24:25], v[242:243] op_sel_hi:[1,0]
	v_pk_mul_f32 v[22:23], v[22:23], v[242:243] op_sel_hi:[1,0]
	v_pk_mul_f32 v[20:21], v[20:21], v[242:243] op_sel_hi:[1,0]
	v_pk_mul_f32 v[18:19], v[18:19], v[242:243] op_sel_hi:[1,0]
	v_pk_mul_f32 v[16:17], v[16:17], v[242:243] op_sel_hi:[1,0]
.Lattn3_nors:
	v_sub_f32_e32 v64, v64, v12
	v_sub_f32_e32 v65, v65, v12
	v_exp_f32_e32 v64, v64
	v_exp_f32_e32 v65, v65
	v_bfe_i32 v246, v158, 0, 1
	v_bfe_i32 v247, v158, 1, 1
	v_and_b32_e32 v64, v64, v246
	v_and_b32_e32 v65, v65, v247
	v_add_f32_e32 v10, v64, v10
	v_add_f32_e32 v10, v65, v10
	v_cvt_pk_bf16_f32 v200, v64, v65
	v_sub_f32_e32 v66, v66, v12
	v_sub_f32_e32 v67, v67, v12
	v_exp_f32_e32 v66, v66
	v_exp_f32_e32 v67, v67
	v_bfe_i32 v246, v158, 2, 1
	v_bfe_i32 v247, v158, 3, 1
	v_and_b32_e32 v66, v66, v246
	v_and_b32_e32 v67, v67, v247
	v_add_f32_e32 v10, v66, v10
	v_add_f32_e32 v10, v67, v10
	v_cvt_pk_bf16_f32 v201, v66, v67
	v_sub_f32_e32 v68, v68, v12
	v_sub_f32_e32 v69, v69, v12
	v_exp_f32_e32 v68, v68
	v_exp_f32_e32 v69, v69
	v_bfe_i32 v246, v158, 8, 1
	v_bfe_i32 v247, v158, 9, 1
	v_and_b32_e32 v68, v68, v246
	v_and_b32_e32 v69, v69, v247
	v_add_f32_e32 v10, v68, v10
	v_add_f32_e32 v10, v69, v10
	v_cvt_pk_bf16_f32 v202, v68, v69
	v_sub_f32_e32 v70, v70, v12
	v_sub_f32_e32 v71, v71, v12
	v_exp_f32_e32 v70, v70
	v_exp_f32_e32 v71, v71
	v_bfe_i32 v246, v158, 10, 1
	v_bfe_i32 v247, v158, 11, 1
	v_and_b32_e32 v70, v70, v246
	v_and_b32_e32 v71, v71, v247
	v_add_f32_e32 v10, v70, v10
	v_add_f32_e32 v10, v71, v10
	v_cvt_pk_bf16_f32 v203, v70, v71
	v_sub_f32_e32 v72, v72, v12
	v_sub_f32_e32 v73, v73, v12
	v_exp_f32_e32 v72, v72
	v_exp_f32_e32 v73, v73
	v_bfe_i32 v246, v158, 16, 1
	v_bfe_i32 v247, v158, 17, 1
	v_and_b32_e32 v72, v72, v246
	v_and_b32_e32 v73, v73, v247
	v_add_f32_e32 v10, v72, v10
	v_add_f32_e32 v10, v73, v10
	v_cvt_pk_bf16_f32 v204, v72, v73
	v_mfma_f32_32x32x16_bf16 v[32:47], v[166:169], v[200:203], v[32:47]
	v_sub_f32_e32 v74, v74, v12
	v_sub_f32_e32 v75, v75, v12
	v_exp_f32_e32 v74, v74
	v_exp_f32_e32 v75, v75
	v_bfe_i32 v246, v158, 18, 1
	v_bfe_i32 v247, v158, 19, 1
	v_and_b32_e32 v74, v74, v246
	v_and_b32_e32 v75, v75, v247
	v_add_f32_e32 v10, v74, v10
	v_add_f32_e32 v10, v75, v10
	v_cvt_pk_bf16_f32 v205, v74, v75
	v_sub_f32_e32 v76, v76, v12
	v_sub_f32_e32 v77, v77, v12
	v_exp_f32_e32 v76, v76
	v_exp_f32_e32 v77, v77
	v_bfe_i32 v246, v158, 24, 1
	v_bfe_i32 v247, v158, 25, 1
	v_and_b32_e32 v76, v76, v246
	v_and_b32_e32 v77, v77, v247
	v_add_f32_e32 v10, v76, v10
	v_add_f32_e32 v10, v77, v10
	v_cvt_pk_bf16_f32 v206, v76, v77
	v_mfma_f32_32x32x16_bf16 v[16:31], v[182:185], v[200:203], v[16:31]
	v_sub_f32_e32 v78, v78, v12
	v_sub_f32_e32 v79, v79, v12
	v_exp_f32_e32 v78, v78
	v_exp_f32_e32 v79, v79
	v_bfe_i32 v246, v158, 26, 1
	v_bfe_i32 v247, v158, 27, 1
	v_and_b32_e32 v78, v78, v246
	v_and_b32_e32 v79, v79, v247
	v_add_f32_e32 v10, v78, v10
	v_add_f32_e32 v10, v79, v10
	v_cvt_pk_bf16_f32 v207, v78, v79
	v_sub_f32_e32 v48, v48, v12
	v_sub_f32_e32 v49, v49, v12
	v_exp_f32_e32 v48, v48
	v_exp_f32_e32 v49, v49
	v_bfe_i32 v246, v159, 0, 1
	v_bfe_i32 v247, v159, 1, 1
	v_and_b32_e32 v48, v48, v246
	v_and_b32_e32 v49, v49, v247
	v_add_f32_e32 v10, v48, v10
	v_add_f32_e32 v10, v49, v10
	v_cvt_pk_bf16_f32 v200, v48, v49
	v_mfma_f32_32x32x16_bf16 v[32:47], v[170:173], v[204:207], v[32:47]
	v_sub_f32_e32 v50, v50, v12
	v_sub_f32_e32 v51, v51, v12
	v_exp_f32_e32 v50, v50
	v_exp_f32_e32 v51, v51
	v_bfe_i32 v246, v159, 2, 1
	v_bfe_i32 v247, v159, 3, 1
	v_and_b32_e32 v50, v50, v246
	v_and_b32_e32 v51, v51, v247
	v_add_f32_e32 v10, v50, v10
	v_add_f32_e32 v10, v51, v10
	v_cvt_pk_bf16_f32 v201, v50, v51
	v_sub_f32_e32 v52, v52, v12
	v_sub_f32_e32 v53, v53, v12
	v_exp_f32_e32 v52, v52
	v_exp_f32_e32 v53, v53
	v_bfe_i32 v246, v159, 8, 1
	v_bfe_i32 v247, v159, 9, 1
	v_and_b32_e32 v52, v52, v246
	v_and_b32_e32 v53, v53, v247
	v_add_f32_e32 v10, v52, v10
	v_add_f32_e32 v10, v53, v10
	v_cvt_pk_bf16_f32 v202, v52, v53
	v_mfma_f32_32x32x16_bf16 v[16:31], v[186:189], v[204:207], v[16:31]
	v_sub_f32_e32 v54, v54, v12
	v_sub_f32_e32 v55, v55, v12
	v_exp_f32_e32 v54, v54
	v_exp_f32_e32 v55, v55
	v_bfe_i32 v246, v159, 10, 1
	v_bfe_i32 v247, v159, 11, 1
	v_and_b32_e32 v54, v54, v246
	v_and_b32_e32 v55, v55, v247
	v_add_f32_e32 v10, v54, v10
	v_add_f32_e32 v10, v55, v10
	v_cvt_pk_bf16_f32 v203, v54, v55
	v_sub_f32_e32 v56, v56, v12
	v_sub_f32_e32 v57, v57, v12
	v_exp_f32_e32 v56, v56
	v_exp_f32_e32 v57, v57
	v_bfe_i32 v246, v159, 16, 1
	v_bfe_i32 v247, v159, 17, 1
	v_and_b32_e32 v56, v56, v246
	v_and_b32_e32 v57, v57, v247
	v_add_f32_e32 v10, v56, v10
	v_add_f32_e32 v10, v57, v10
	v_cvt_pk_bf16_f32 v204, v56, v57
	v_mfma_f32_32x32x16_bf16 v[32:47], v[174:177], v[200:203], v[32:47]
	v_sub_f32_e32 v58, v58, v12
	v_sub_f32_e32 v59, v59, v12
	v_exp_f32_e32 v58, v58
	v_exp_f32_e32 v59, v59
	v_bfe_i32 v246, v159, 18, 1
	v_bfe_i32 v247, v159, 19, 1
	v_and_b32_e32 v58, v58, v246
	v_and_b32_e32 v59, v59, v247
	v_add_f32_e32 v10, v58, v10
	v_add_f32_e32 v10, v59, v10
	v_cvt_pk_bf16_f32 v205, v58, v59
	v_sub_f32_e32 v60, v60, v12
	v_sub_f32_e32 v61, v61, v12
	v_exp_f32_e32 v60, v60
	v_exp_f32_e32 v61, v61
	v_bfe_i32 v246, v159, 24, 1
	v_bfe_i32 v247, v159, 25, 1
	v_and_b32_e32 v60, v60, v246
	v_and_b32_e32 v61, v61, v247
	v_add_f32_e32 v10, v60, v10
	v_add_f32_e32 v10, v61, v10
	v_cvt_pk_bf16_f32 v206, v60, v61
	v_mfma_f32_32x32x16_bf16 v[16:31], v[190:193], v[200:203], v[16:31]
	v_sub_f32_e32 v62, v62, v12
	v_sub_f32_e32 v63, v63, v12
	v_exp_f32_e32 v62, v62
	v_exp_f32_e32 v63, v63
	v_bfe_i32 v246, v159, 26, 1
	v_bfe_i32 v247, v159, 27, 1
	v_and_b32_e32 v62, v62, v246
	v_and_b32_e32 v63, v63, v247
	v_add_f32_e32 v10, v62, v10
	v_add_f32_e32 v10, v63, v10
	v_cvt_pk_bf16_f32 v207, v62, v63
	v_cmp_eq_u32_e32 vcc, s18, v111
	v_add_u32_e32 v152, 8, v152
	v_fmac_f32_e32 v10, v153, v242
	v_mfma_f32_32x32x16_bf16 v[32:47], v[178:181], v[204:207], v[32:47]
	s_or_b64 s[14:15], vcc, s[14:15]
	s_mov_b32 s19, s18
	v_mov_b32_e32 v154, v12
	v_mov_b32_e32 v153, v10
	s_barrier
	v_mfma_f32_32x32x16_bf16 v[16:31], v[194:197], v[204:207], v[16:31]
	s_waitcnt vmcnt(0)
	v_mov_b64_e32 v[48:49], v[96:97]
	v_mov_b64_e32 v[52:53], v[100:101]
	v_mov_b64_e32 v[50:51], v[98:99]
	v_mov_b64_e32 v[54:55], v[102:103]
	v_mov_b64_e32 v[98:99], v[4:5]
	v_mov_b64_e32 v[102:103], v[8:9]
	v_mov_b64_e32 v[96:97], v[2:3]
	v_mov_b64_e32 v[100:101], v[6:7]
	s_andn2_b64 exec, exec, s[14:15]
	s_cbranch_execz .LBB0_759
	s_branch .LBB0_803
